# baseline (speedup 1.0000x reference)
; __device__ __forceinline__ unsigned xb_add(unsigned* p, unsigned v) { return __hip_atomic_fetch_add(p, v, __ATOMIC_RELAXED, __HIP_MEMORY_SCOPE_AGENT); }
; __device__ __forceinline__ void xcd_barrier(unsigned* bar, volatile LAS unsigned* st) {
;     ...
;             xb_add(&bar[XB_XGEN(x)], 1u);
;             __builtin_amdgcn_fence(__ATOMIC_ACQUIRE, "agent");
;             asm volatile("s_waitcnt vmcnt(0)" ::: "memory");
.Lxl_skip_gu:
	v_mov_b32_e32 v0, 1
	v_mov_b32_e32 v2, 0x2000
	global_atomic_add v2, v0, s[8:9] offset:1024
	s_waitcnt vmcnt(1)
	s_branch .LBB0_362

; __device__ __forceinline__ unsigned xb_add(unsigned* p, unsigned v) { return __hip_atomic_fetch_add(p, v, __ATOMIC_RELAXED, __HIP_MEMORY_SCOPE_AGENT); }
; __device__ __forceinline__ void xcd_barrier(unsigned* bar, volatile LAS unsigned* st) {
;     ...
;             xb_add(&bar[XB_XGEN(x)], 1u);
;             __builtin_amdgcn_fence(__ATOMIC_ACQUIRE, "agent");
;             asm volatile("s_waitcnt vmcnt(0)" ::: "memory");
.Lxl_skip_d:
	v_mov_b32_e32 v0, 1
	v_mov_b32_e32 v2, 0x2000
	global_atomic_add v2, v0, s[10:11] offset:1024
	s_waitcnt vmcnt(1)
	s_branch .LBB0_455
